# grid barrier: non-leader workgroups poll TOPGEN directly, XGEN relay hop removed
# speedup vs baseline: 1.0027x; 1.0027x over previous
; __device__ __forceinline__ unsigned xb_ld(unsigned* p)              { return __hip_atomic_load(p, __ATOMIC_RELAXED, __HIP_MEMORY_SCOPE_AGENT); }
; __device__ __forceinline__ unsigned xb_add(unsigned* p, unsigned v) { return __hip_atomic_fetch_add(p, v, __ATOMIC_RELAXED, __HIP_MEMORY_SCOPE_AGENT); }
; #define XB_SPIN(cond, bar) do { unsigned _sp = 0; while (cond) { __builtin_amdgcn_s_sleep(1); \
;     if ((++_sp & 255u) == 0u) { if (xb_ld(&(bar)[XB_TMO])) break; if (_sp > XB_SPIN_CAP) { atomicAdd(&(bar)[XB_TMO], 1u); break; } } } } while (0)
; __device__ __forceinline__ void xcd_barrier(const XcdBarrier& b, const int tid) {
;     ...
;         const unsigned old = xb_add(&bar[XB_XSUB(b.x)], 1u);
;         const unsigned gen = old / nloc;
;         if (old + 1u == (gen + 1u) * nloc) {
;             __builtin_amdgcn_fence(__ATOMIC_RELEASE, "agent");
;             asm volatile("s_waitcnt vmcnt(0)" ::: "memory");
;             const unsigned og = xb_add(&bar[XB_TOP], 1u);
;             const unsigned tg = og / nx;
;             if (og + 1u == (tg + 1u) * nx) xb_add(&bar[XB_TOPGEN], 1u);
;             else XB_SPIN(xb_ld(&bar[XB_TOPGEN]) == tg, bar);
;             __builtin_amdgcn_fence(__ATOMIC_ACQUIRE, "agent");
;             xb_add(&bar[XB_XGEN(b.x)], 1u);
;             asm volatile("s_waitcnt vmcnt(0)" ::: "memory");
;         } else {
;             XB_SPIN(xb_ld(&bar[XB_XGEN(b.x)]) == gen, bar);
.LBB0_40:
	s_or_b64 exec, exec, s[6:7]
	v_cvt_f32_u32_e32 v5, v3
	s_waitcnt vmcnt(0)
	v_readfirstlane_b32 s4, v4
	v_sub_u32_e32 v4, 0, v3
	v_rcp_iflag_f32_e32 v5, v5
	v_add_u32_e32 v6, s4, v1
	v_mul_f32_e32 v5, 0x4f7ffffe, v5
	v_cvt_u32_f32_e32 v5, v5
	v_mul_lo_u32 v1, v4, v5
	v_mul_hi_u32 v1, v5, v1
	v_add_u32_e32 v1, v5, v1
	v_mul_hi_u32 v1, v6, v1
	v_mul_lo_u32 v4, v1, v3
	v_sub_u32_e32 v4, v6, v4
	v_add_u32_e32 v5, 1, v1
	v_cmp_ge_u32_e32 vcc, v4, v3
	s_nop 1
	v_cndmask_b32_e32 v1, v1, v5, vcc
	v_sub_u32_e32 v5, v4, v3
	v_cndmask_b32_e32 v4, v4, v5, vcc
	v_add_u32_e32 v5, 1, v1
	v_cmp_ge_u32_e32 vcc, v4, v3
	v_add_u32_e32 v4, 1, v6
	s_nop 0
	v_cndmask_b32_e32 v1, v1, v5, vcc
	v_mul_lo_u32 v5, v3, v1
	v_add_u32_e32 v3, v5, v3
	v_cmp_ne_u32_e32 vcc, v4, v3
	s_and_saveexec_b64 s[4:5], vcc
	s_xor_b64 s[4:5], exec, s[4:5]
	s_cbranch_execz .LBB0_54
	s_waitcnt lgkmcnt(0)
	s_add_u32 s10, s22, 0x11d03500
	s_addc_u32 s11, s23, 0
	global_load_dword v2, v179, s[10:11] sc1
	s_nop 0
	s_waitcnt vmcnt(0)
	v_cmp_eq_u32_e32 vcc, v2, v1
	s_and_saveexec_b64 s[6:7], vcc
	s_cbranch_execz .LBB0_53
	s_add_u32 s8, s22, 0x11d00200
	s_addc_u32 s9, s23, 0
	s_mov_b32 s24, 1
	s_mov_b64 s[12:13], 0
	s_branch .LBB0_44

; __device__ __forceinline__ unsigned xb_ld(unsigned* p)              { return __hip_atomic_load(p, __ATOMIC_RELAXED, __HIP_MEMORY_SCOPE_AGENT); }
; __device__ __forceinline__ unsigned xb_add(unsigned* p, unsigned v) { return __hip_atomic_fetch_add(p, v, __ATOMIC_RELAXED, __HIP_MEMORY_SCOPE_AGENT); }
; #define XB_SPIN(cond, bar) do { unsigned _sp = 0; while (cond) { __builtin_amdgcn_s_sleep(1); \
;     if ((++_sp & 255u) == 0u) { if (xb_ld(&(bar)[XB_TMO])) break; if (_sp > XB_SPIN_CAP) { atomicAdd(&(bar)[XB_TMO], 1u); break; } } } } while (0)
; __device__ __forceinline__ void xcd_barrier(const XcdBarrier& b, const int tid) {
;     ...
;             else XB_SPIN(xb_ld(&bar[XB_TOPGEN]) == tg, bar);
;             __builtin_amdgcn_fence(__ATOMIC_ACQUIRE, "agent");
;             xb_add(&bar[XB_XGEN(b.x)], 1u);
;             asm volatile("s_waitcnt vmcnt(0)" ::: "memory");
.LBB0_71:
	s_or_b64 exec, exec, s[4:5]
	s_mov_b64 s[4:5], exec
	v_mbcnt_lo_u32_b32 v1, s4, 0
	v_mbcnt_hi_u32_b32 v1, s5, v1
	v_cmp_eq_u32_e32 vcc, 0, v1
	s_waitcnt vmcnt(0)
	buffer_inv sc1
	s_and_saveexec_b64 s[6:7], vcc
	s_cbranch_execz .LBB0_73
	s_bcnt1_i32_b64 s4, s[4:5]
	v_mov_b32_e32 v1, s4
	v_mov_b32_e32 v2, 0x2000
.LBB0_73:
	s_or_b64 exec, exec, s[6:7]
	s_waitcnt vmcnt(0)
